# P4 epilogue: both 128-row halves' residual-stream loads issued together up front (second half no longer waits behind the first half's stores)
# baseline (speedup 1.0000x reference)
; __device__ __forceinline__ u32x4 pack8h(const f32x4 a, const f32x4 b) { u32x4 w; w.x = cvt_pk_f16(a[0], a[1]); w.y = cvt_pk_f16(a[2], a[3]); w.z = cvt_pk_f16(b[0], b[1]); w.w = cvt_pk_f16(b[2], b[3]); return w; }
; #define PG8_FENCE asm volatile("" ::: "memory")
;     __device__ __forceinline__ void operator()(const f32x4 (&acc)[2][2][4][2], const Unit& u, int wr, int wc, int fr, int fq) const {
;     ...
;         for (int ai = 0; ai < 2; ++ai) {
;             u32x4 wx[4][2];
; #pragma unroll
;             for (int m = 0; m < 4; ++m) { const size_t off = (size_t)(row0 + ai * HALF + m * 16) * 1024 + c0;
; #pragma unroll
;                 for (int bj = 0; bj < 2; ++bj) wx[m][bj] = *(const u32x4*)(XH + off + bj * HALF); }
;             PG8_FENCE;
; #pragma unroll
;             for (int m = 0; m < 4; ++m) { const size_t off = (size_t)(row0 + ai * HALF + m * 16) * 1024 + c0;
; #pragma unroll
;                 for (int bj = 0; bj < 2; ++bj) { f32x4 r0, r1; unpack8h(wx[m][bj], r0, r1);
;                     const f32x4 h0 = r0 * alpha + acc[ai][bj][m][0], h1 = r1 * alpha + acc[ai][bj][m][1];
;                     *(u32x4*)(XO + off + bj * HALF) = pack8h(h0, h1); } }
.LBB0_852:
	s_lshl_b32 s10, s10, 8
	v_mov_b32_e32 v131, v173
	v_mov_b32_e32 v130, v172
	s_lshl_b32 s11, s11, 8
	s_or_b32 s10, s10, s48
	s_add_i32 s11, s11, s47
	v_lshl_add_u32 v132, v131, 3, s10
	v_add_u32_e32 v130, s11, v130
	v_ashrrev_i32_e32 v133, 31, v132
	v_lshlrev_b64 v[160:161], 1, v[132:133]
	v_ashrrev_i32_e32 v131, 31, v130
	v_lshl_add_u64 v[162:163], s[4:5], 0, v[160:161]
	v_lshlrev_b64 v[164:165], 11, v[130:131]
	v_lshl_add_u64 v[130:131], v[162:163], 0, v[164:165]
	global_load_dwordx4 v[176:179], v[130:131], off
	global_load_dwordx4 v[180:183], v[130:131], off offset:256
	s_mov_b64 s[10:11], 0x8000
	v_lshl_add_u64 v[170:171], v[164:165], 0, s[10:11]
	v_lshl_add_u64 v[130:131], v[162:163], 0, v[170:171]
	global_load_dwordx4 v[184:187], v[130:131], off
	global_load_dwordx4 v[146:149], v[130:131], off offset:256
	s_mov_b64 s[10:11], 0x10000
	v_lshl_add_u64 v[168:169], v[164:165], 0, s[10:11]
	v_lshl_add_u64 v[130:131], v[162:163], 0, v[168:169]
	global_load_dwordx4 v[142:145], v[130:131], off
	global_load_dwordx4 v[138:141], v[130:131], off offset:256
	s_mov_b64 s[10:11], 0x18000
	v_lshl_add_u64 v[166:167], v[164:165], 0, s[10:11]
	v_lshl_add_u64 v[130:131], v[162:163], 0, v[166:167]
	global_load_dwordx4 v[134:137], v[130:131], off
	s_nop 0
	global_load_dwordx4 v[130:133], v[130:131], off offset:256
	s_mov_b64 s[98:99], 0x40000
	v_lshl_add_u64 v[246:247], v[164:165], 0, s[98:99]
	v_lshl_add_u64 v[246:247], v[162:163], 0, v[246:247]
	global_load_dwordx4 v[248:251], v[246:247], off
	global_load_dwordx4 v[206:209], v[246:247], off offset:256
	s_mov_b64 s[98:99], 0x48000
	v_lshl_add_u64 v[246:247], v[164:165], 0, s[98:99]
	v_lshl_add_u64 v[246:247], v[162:163], 0, v[246:247]
	global_load_dwordx4 v[210:213], v[246:247], off
	global_load_dwordx4 v[214:217], v[246:247], off offset:256
	s_mov_b64 s[98:99], 0x50000
	v_lshl_add_u64 v[246:247], v[164:165], 0, s[98:99]
	v_lshl_add_u64 v[246:247], v[162:163], 0, v[246:247]
	global_load_dwordx4 v[218:221], v[246:247], off
	global_load_dwordx4 v[222:225], v[246:247], off offset:256
	s_mov_b64 s[98:99], 0x58000
	v_lshl_add_u64 v[246:247], v[164:165], 0, s[98:99]
	v_lshl_add_u64 v[246:247], v[162:163], 0, v[246:247]
	global_load_dwordx4 v[226:229], v[246:247], off
	global_load_dwordx4 v[242:245], v[246:247], off offset:256
	s_mov_b32 s24, 0x3fd744fd
	s_mov_b64 s[10:11], 0x40000
	v_readlane_b32 s30, v255, 10
	s_andn2_b64 vcc, exec, s[38:39]
	v_readlane_b32 s31, v255, 11
	s_waitcnt vmcnt(8)
	v_cvt_f32_f16_e32 v188, v176
	v_cvt_f32_f16_sdwa v189, v176 dst_sel:DWORD dst_unused:UNUSED_PAD src0_sel:WORD_1
	v_cvt_f32_f16_e32 v176, v177
	v_cvt_f32_f16_sdwa v177, v177 dst_sel:DWORD dst_unused:UNUSED_PAD src0_sel:WORD_1
	v_cvt_f32_f16_e32 v190, v178
	v_cvt_f32_f16_sdwa v191, v178 dst_sel:DWORD dst_unused:UNUSED_PAD src0_sel:WORD_1
	v_cvt_f32_f16_e32 v178, v179
	v_cvt_f32_f16_sdwa v179, v179 dst_sel:DWORD dst_unused:UNUSED_PAD src0_sel:WORD_1
	v_pk_fma_f32 v[126:127], v[188:189], s[24:25], v[126:127] op_sel_hi:[1,0,1]
	v_pk_fma_f32 v[128:129], v[176:177], s[24:25], v[128:129] op_sel_hi:[1,0,1]
	v_pk_fma_f32 v[176:177], v[178:179], s[24:25], v[124:125] op_sel_hi:[1,0,1]
	v_pk_fma_f32 v[124:125], v[190:191], s[24:25], v[122:123] op_sel_hi:[1,0,1]
	v_cvt_pk_f16_f32 v122, v126, v127
	v_lshl_add_u64 v[126:127], s[2:3], 0, v[164:165]
	v_cvt_pk_f16_f32 v123, v128, v129
	v_cvt_pk_f16_f32 v124, v124, v125
	v_cvt_pk_f16_f32 v125, v176, v177
	v_lshl_add_u64 v[126:127], v[126:127], 0, v[160:161]
	global_store_dwordx4 v[126:127], v[122:125], off
	v_cvt_f32_f16_e32 v128, v182
	v_cvt_f32_f16_sdwa v129, v182 dst_sel:DWORD dst_unused:UNUSED_PAD src0_sel:WORD_1
	v_cvt_f32_f16_e32 v122, v180
	v_cvt_f32_f16_sdwa v123, v180 dst_sel:DWORD dst_unused:UNUSED_PAD src0_sel:WORD_1
	v_cvt_f32_f16_e32 v124, v181
	v_cvt_f32_f16_sdwa v125, v181 dst_sel:DWORD dst_unused:UNUSED_PAD src0_sel:WORD_1
	v_cvt_f32_f16_e32 v176, v183
	v_cvt_f32_f16_sdwa v177, v183 dst_sel:DWORD dst_unused:UNUSED_PAD src0_sel:WORD_1
	v_pk_fma_f32 v[110:111], v[122:123], s[24:25], v[110:111] op_sel_hi:[1,0,1]
	v_pk_fma_f32 v[112:113], v[124:125], s[24:25], v[112:113] op_sel_hi:[1,0,1]
	v_pk_fma_f32 v[122:123], v[176:177], s[24:25], v[108:109] op_sel_hi:[1,0,1]
	v_pk_fma_f32 v[108:109], v[128:129], s[24:25], v[106:107] op_sel_hi:[1,0,1]
	v_cvt_pk_f16_f32 v106, v110, v111
	v_cvt_pk_f16_f32 v107, v112, v113
	v_cvt_pk_f16_f32 v108, v108, v109
	v_cvt_pk_f16_f32 v109, v122, v123
	global_store_dwordx4 v[126:127], v[106:109], off offset:256
	v_cvt_f32_f16_e32 v110, v186
	v_cvt_f32_f16_sdwa v111, v186 dst_sel:DWORD dst_unused:UNUSED_PAD src0_sel:WORD_1
	v_cvt_f32_f16_e32 v106, v184
	v_cvt_f32_f16_sdwa v107, v184 dst_sel:DWORD dst_unused:UNUSED_PAD src0_sel:WORD_1
	v_cvt_f32_f16_e32 v108, v185
	v_cvt_f32_f16_sdwa v109, v185 dst_sel:DWORD dst_unused:UNUSED_PAD src0_sel:WORD_1
	v_cvt_f32_f16_e32 v112, v187
	v_cvt_f32_f16_sdwa v113, v187 dst_sel:DWORD dst_unused:UNUSED_PAD src0_sel:WORD_1
	v_pk_fma_f32 v[106:107], v[106:107], s[24:25], v[118:119] op_sel_hi:[1,0,1]
	v_pk_fma_f32 v[108:109], v[108:109], s[24:25], v[120:121] op_sel_hi:[1,0,1]
	v_pk_fma_f32 v[110:111], v[110:111], s[24:25], v[114:115] op_sel_hi:[1,0,1]
	v_pk_fma_f32 v[112:113], v[112:113], s[24:25], v[116:117] op_sel_hi:[1,0,1]
	v_cvt_pk_f16_f32 v106, v106, v107
	v_cvt_pk_f16_f32 v107, v108, v109
	v_cvt_pk_f16_f32 v108, v110, v111
	v_lshl_add_u64 v[110:111], s[2:3], 0, v[170:171]
	v_cvt_pk_f16_f32 v109, v112, v113
	v_lshl_add_u64 v[110:111], v[110:111], 0, v[160:161]
	global_store_dwordx4 v[110:111], v[106:109], off
	v_cvt_f32_f16_e32 v112, v148
	v_cvt_f32_f16_sdwa v113, v148 dst_sel:DWORD dst_unused:UNUSED_PAD src0_sel:WORD_1
; __device__ __forceinline__ u32x4 pack8h(const f32x4 a, const f32x4 b) { u32x4 w; w.x = cvt_pk_f16(a[0], a[1]); w.y = cvt_pk_f16(a[2], a[3]); w.z = cvt_pk_f16(b[0], b[1]); w.w = cvt_pk_f16(b[2], b[3]); return w; }
;     __device__ __forceinline__ void operator()(const f32x4 (&acc)[2][2][4][2], const Unit& u, int wr, int wc, int fr, int fq) const {
;     ...
; #pragma unroll
;             for (int m = 0; m < 4; ++m) { const size_t off = (size_t)(row0 + ai * HALF + m * 16) * 1024 + c0;
; #pragma unroll
;                 for (int bj = 0; bj < 2; ++bj) { f32x4 r0, r1; unpack8h(wx[m][bj], r0, r1);
;                     const f32x4 h0 = r0 * alpha + acc[ai][bj][m][0], h1 = r1 * alpha + acc[ai][bj][m][1];
;                     *(u32x4*)(XO + off + bj * HALF) = pack8h(h0, h1); } }
	v_cvt_f32_f16_e32 v106, v146
	v_cvt_f32_f16_sdwa v107, v146 dst_sel:DWORD dst_unused:UNUSED_PAD src0_sel:WORD_1
	v_cvt_f32_f16_e32 v108, v147
	v_cvt_f32_f16_sdwa v109, v147 dst_sel:DWORD dst_unused:UNUSED_PAD src0_sel:WORD_1
	v_cvt_f32_f16_e32 v114, v149
	v_cvt_f32_f16_sdwa v115, v149 dst_sel:DWORD dst_unused:UNUSED_PAD src0_sel:WORD_1
	v_pk_fma_f32 v[102:103], v[106:107], s[24:25], v[102:103] op_sel_hi:[1,0,1]
	v_pk_fma_f32 v[104:105], v[108:109], s[24:25], v[104:105] op_sel_hi:[1,0,1]
	v_pk_fma_f32 v[106:107], v[114:115], s[24:25], v[100:101] op_sel_hi:[1,0,1]
	v_pk_fma_f32 v[100:101], v[112:113], s[24:25], v[98:99] op_sel_hi:[1,0,1]
	v_cvt_pk_f16_f32 v98, v102, v103
	v_cvt_pk_f16_f32 v99, v104, v105
	v_cvt_pk_f16_f32 v100, v100, v101
	v_cvt_pk_f16_f32 v101, v106, v107
	global_store_dwordx4 v[110:111], v[98:101], off offset:256
	v_cvt_f32_f16_e32 v102, v144
	v_cvt_f32_f16_sdwa v103, v144 dst_sel:DWORD dst_unused:UNUSED_PAD src0_sel:WORD_1
	v_cvt_f32_f16_e32 v98, v142
	v_cvt_f32_f16_sdwa v99, v142 dst_sel:DWORD dst_unused:UNUSED_PAD src0_sel:WORD_1
	v_cvt_f32_f16_e32 v100, v143
	v_cvt_f32_f16_sdwa v101, v143 dst_sel:DWORD dst_unused:UNUSED_PAD src0_sel:WORD_1
	v_cvt_f32_f16_e32 v104, v145
	v_cvt_f32_f16_sdwa v105, v145 dst_sel:DWORD dst_unused:UNUSED_PAD src0_sel:WORD_1
	v_pk_fma_f32 v[94:95], v[98:99], s[24:25], v[94:95] op_sel_hi:[1,0,1]
	v_pk_fma_f32 v[96:97], v[100:101], s[24:25], v[96:97] op_sel_hi:[1,0,1]
	v_lshl_add_u64 v[100:101], v[164:165], 0, s[10:11]
	v_pk_fma_f32 v[98:99], v[104:105], s[24:25], v[92:93] op_sel_hi:[1,0,1]
	v_pk_fma_f32 v[92:93], v[102:103], s[24:25], v[90:91] op_sel_hi:[1,0,1]
	v_cvt_pk_f16_f32 v90, v94, v95
	v_lshl_add_u64 v[94:95], s[2:3], 0, v[168:169]
	v_cvt_pk_f16_f32 v91, v96, v97
	v_cvt_pk_f16_f32 v92, v92, v93
	v_cvt_pk_f16_f32 v93, v98, v99
	v_lshl_add_u64 v[94:95], v[94:95], 0, v[160:161]
	global_store_dwordx4 v[94:95], v[90:93], off
	v_cvt_f32_f16_e32 v96, v140
	v_cvt_f32_f16_sdwa v97, v140 dst_sel:DWORD dst_unused:UNUSED_PAD src0_sel:WORD_1
	v_cvt_f32_f16_e32 v90, v138
	v_cvt_f32_f16_sdwa v91, v138 dst_sel:DWORD dst_unused:UNUSED_PAD src0_sel:WORD_1
	v_cvt_f32_f16_e32 v92, v139
	v_cvt_f32_f16_sdwa v93, v139 dst_sel:DWORD dst_unused:UNUSED_PAD src0_sel:WORD_1
	v_cvt_f32_f16_e32 v98, v141
	v_cvt_f32_f16_sdwa v99, v141 dst_sel:DWORD dst_unused:UNUSED_PAD src0_sel:WORD_1
	v_pk_fma_f32 v[86:87], v[90:91], s[24:25], v[86:87] op_sel_hi:[1,0,1]
	v_pk_fma_f32 v[88:89], v[92:93], s[24:25], v[88:89] op_sel_hi:[1,0,1]
	s_mov_b64 s[10:11], 0x48000
	v_pk_fma_f32 v[90:91], v[98:99], s[24:25], v[84:85] op_sel_hi:[1,0,1]
	v_pk_fma_f32 v[84:85], v[96:97], s[24:25], v[82:83] op_sel_hi:[1,0,1]
	v_cvt_pk_f16_f32 v82, v86, v87
	v_cvt_pk_f16_f32 v83, v88, v89
	v_cvt_pk_f16_f32 v84, v84, v85
	v_cvt_pk_f16_f32 v85, v90, v91
	global_store_dwordx4 v[94:95], v[82:85], off offset:256
	v_cvt_f32_f16_e32 v86, v136
	v_cvt_f32_f16_sdwa v87, v136 dst_sel:DWORD dst_unused:UNUSED_PAD src0_sel:WORD_1
	v_cvt_f32_f16_e32 v82, v134
	v_cvt_f32_f16_sdwa v83, v134 dst_sel:DWORD dst_unused:UNUSED_PAD src0_sel:WORD_1
	v_cvt_f32_f16_e32 v84, v135
	v_cvt_f32_f16_sdwa v85, v135 dst_sel:DWORD dst_unused:UNUSED_PAD src0_sel:WORD_1
	v_cvt_f32_f16_e32 v88, v137
	v_cvt_f32_f16_sdwa v89, v137 dst_sel:DWORD dst_unused:UNUSED_PAD src0_sel:WORD_1
	v_pk_fma_f32 v[78:79], v[82:83], s[24:25], v[78:79] op_sel_hi:[1,0,1]
	v_pk_fma_f32 v[80:81], v[84:85], s[24:25], v[80:81] op_sel_hi:[1,0,1]
	v_lshl_add_u64 v[102:103], v[164:165], 0, s[10:11]
	v_pk_fma_f32 v[82:83], v[88:89], s[24:25], v[76:77] op_sel_hi:[1,0,1]
	v_pk_fma_f32 v[76:77], v[86:87], s[24:25], v[74:75] op_sel_hi:[1,0,1]
	v_cvt_pk_f16_f32 v74, v78, v79
	v_lshl_add_u64 v[78:79], s[2:3], 0, v[166:167]
	v_cvt_pk_f16_f32 v75, v80, v81
	v_cvt_pk_f16_f32 v76, v76, v77
	v_cvt_pk_f16_f32 v77, v82, v83
	v_lshl_add_u64 v[78:79], v[78:79], 0, v[160:161]
	global_store_dwordx4 v[78:79], v[74:77], off
	v_cvt_f32_f16_e32 v80, v132
	v_cvt_f32_f16_sdwa v81, v132 dst_sel:DWORD dst_unused:UNUSED_PAD src0_sel:WORD_1
	v_cvt_f32_f16_e32 v74, v130
	v_cvt_f32_f16_sdwa v75, v130 dst_sel:DWORD dst_unused:UNUSED_PAD src0_sel:WORD_1
	v_cvt_f32_f16_e32 v76, v131
	v_cvt_f32_f16_sdwa v77, v131 dst_sel:DWORD dst_unused:UNUSED_PAD src0_sel:WORD_1
	v_cvt_f32_f16_e32 v82, v133
	v_cvt_f32_f16_sdwa v83, v133 dst_sel:DWORD dst_unused:UNUSED_PAD src0_sel:WORD_1
	v_pk_fma_f32 v[70:71], v[74:75], s[24:25], v[70:71] op_sel_hi:[1,0,1]
	v_pk_fma_f32 v[72:73], v[76:77], s[24:25], v[72:73] op_sel_hi:[1,0,1]
	s_mov_b64 s[10:11], 0x50000
	v_pk_fma_f32 v[74:75], v[82:83], s[24:25], v[68:69] op_sel_hi:[1,0,1]
	v_pk_fma_f32 v[68:69], v[80:81], s[24:25], v[66:67] op_sel_hi:[1,0,1]
	v_cvt_pk_f16_f32 v66, v70, v71
	v_cvt_pk_f16_f32 v67, v72, v73
	v_cvt_pk_f16_f32 v68, v68, v69
	v_cvt_pk_f16_f32 v69, v74, v75
	global_store_dwordx4 v[78:79], v[66:69], off offset:256
	v_lshl_add_u64 v[104:105], v[164:165], 0, s[10:11]
	s_mov_b64 s[10:11], 0x58000
	v_lshl_add_u64 v[66:67], v[162:163], 0, v[100:101]
	v_lshl_add_u64 v[66:67], v[162:163], 0, v[102:103]
	v_lshl_add_u64 v[66:67], v[162:163], 0, v[104:105]
	v_lshl_add_u64 v[74:75], v[164:165], 0, s[10:11]
	v_lshl_add_u64 v[66:67], v[162:163], 0, v[74:75]
	s_nop 0
	s_waitcnt vmcnt(15)
; __device__ __forceinline__ u32x4 pack8h(const f32x4 a, const f32x4 b) { u32x4 w; w.x = cvt_pk_f16(a[0], a[1]); w.y = cvt_pk_f16(a[2], a[3]); w.z = cvt_pk_f16(b[0], b[1]); w.w = cvt_pk_f16(b[2], b[3]); return w; }
;     __device__ __forceinline__ void operator()(const f32x4 (&acc)[2][2][4][2], const Unit& u, int wr, int wc, int fr, int fq) const {
;     ...
; #pragma unroll
;             for (int m = 0; m < 4; ++m) { const size_t off = (size_t)(row0 + ai * HALF + m * 16) * 1024 + c0;
; #pragma unroll
;                 for (int bj = 0; bj < 2; ++bj) { f32x4 r0, r1; unpack8h(wx[m][bj], r0, r1);
;                     const f32x4 h0 = r0 * alpha + acc[ai][bj][m][0], h1 = r1 * alpha + acc[ai][bj][m][1];
;                     *(u32x4*)(XO + off + bj * HALF) = pack8h(h0, h1); } }
	v_cvt_f32_f16_e32 v106, v248
	v_cvt_f32_f16_sdwa v107, v248 dst_sel:DWORD dst_unused:UNUSED_PAD src0_sel:WORD_1
	v_cvt_f32_f16_e32 v76, v249
	v_cvt_f32_f16_sdwa v77, v249 dst_sel:DWORD dst_unused:UNUSED_PAD src0_sel:WORD_1
	v_cvt_f32_f16_e32 v108, v250
	v_cvt_f32_f16_sdwa v109, v250 dst_sel:DWORD dst_unused:UNUSED_PAD src0_sel:WORD_1
	v_cvt_f32_f16_e32 v78, v251
	v_cvt_f32_f16_sdwa v79, v251 dst_sel:DWORD dst_unused:UNUSED_PAD src0_sel:WORD_1
	v_pk_fma_f32 v[60:61], v[106:107], s[24:25], v[60:61] op_sel_hi:[1,0,1]
	v_pk_fma_f32 v[62:63], v[76:77], s[24:25], v[62:63] op_sel_hi:[1,0,1]
	v_pk_fma_f32 v[76:77], v[78:79], s[24:25], v[58:59] op_sel_hi:[1,0,1]
	v_pk_fma_f32 v[58:59], v[108:109], s[24:25], v[56:57] op_sel_hi:[1,0,1]
	v_cvt_pk_f16_f32 v56, v60, v61
	v_lshl_add_u64 v[60:61], s[2:3], 0, v[100:101]
	v_cvt_pk_f16_f32 v57, v62, v63
	v_cvt_pk_f16_f32 v58, v58, v59
	v_cvt_pk_f16_f32 v59, v76, v77
	v_lshl_add_u64 v[60:61], v[60:61], 0, v[160:161]
	global_store_dwordx4 v[60:61], v[56:59], off
	s_waitcnt vmcnt(15)
	v_cvt_f32_f16_e32 v62, v208
	v_cvt_f32_f16_sdwa v63, v208 dst_sel:DWORD dst_unused:UNUSED_PAD src0_sel:WORD_1
	v_cvt_f32_f16_e32 v56, v206
	v_cvt_f32_f16_sdwa v57, v206 dst_sel:DWORD dst_unused:UNUSED_PAD src0_sel:WORD_1
	v_cvt_f32_f16_e32 v58, v207
	v_cvt_f32_f16_sdwa v59, v207 dst_sel:DWORD dst_unused:UNUSED_PAD src0_sel:WORD_1
	v_cvt_f32_f16_e32 v76, v209
	v_cvt_f32_f16_sdwa v77, v209 dst_sel:DWORD dst_unused:UNUSED_PAD src0_sel:WORD_1
	v_pk_fma_f32 v[52:53], v[56:57], s[24:25], v[52:53] op_sel_hi:[1,0,1]
	v_pk_fma_f32 v[54:55], v[58:59], s[24:25], v[54:55] op_sel_hi:[1,0,1]
	v_pk_fma_f32 v[56:57], v[76:77], s[24:25], v[50:51] op_sel_hi:[1,0,1]
	v_pk_fma_f32 v[50:51], v[62:63], s[24:25], v[48:49] op_sel_hi:[1,0,1]
	v_cvt_pk_f16_f32 v48, v52, v53
	v_cvt_pk_f16_f32 v49, v54, v55
	v_cvt_pk_f16_f32 v50, v50, v51
	v_cvt_pk_f16_f32 v51, v56, v57
	global_store_dwordx4 v[60:61], v[48:51], off offset:256
	s_waitcnt vmcnt(15)
	v_cvt_f32_f16_e32 v52, v212
	v_cvt_f32_f16_sdwa v53, v212 dst_sel:DWORD dst_unused:UNUSED_PAD src0_sel:WORD_1
	v_cvt_f32_f16_e32 v48, v210
	v_cvt_f32_f16_sdwa v49, v210 dst_sel:DWORD dst_unused:UNUSED_PAD src0_sel:WORD_1
	v_cvt_f32_f16_e32 v50, v211
	v_cvt_f32_f16_sdwa v51, v211 dst_sel:DWORD dst_unused:UNUSED_PAD src0_sel:WORD_1
	v_cvt_f32_f16_e32 v54, v213
	v_cvt_f32_f16_sdwa v55, v213 dst_sel:DWORD dst_unused:UNUSED_PAD src0_sel:WORD_1
	v_pk_fma_f32 v[44:45], v[48:49], s[24:25], v[44:45] op_sel_hi:[1,0,1]
	v_pk_fma_f32 v[46:47], v[50:51], s[24:25], v[46:47] op_sel_hi:[1,0,1]
	v_pk_fma_f32 v[48:49], v[54:55], s[24:25], v[42:43] op_sel_hi:[1,0,1]
	v_pk_fma_f32 v[42:43], v[52:53], s[24:25], v[40:41] op_sel_hi:[1,0,1]
	v_cvt_pk_f16_f32 v40, v44, v45
	v_lshl_add_u64 v[44:45], s[2:3], 0, v[102:103]
	v_cvt_pk_f16_f32 v41, v46, v47
	v_cvt_pk_f16_f32 v42, v42, v43
	v_cvt_pk_f16_f32 v43, v48, v49
	v_lshl_add_u64 v[44:45], v[44:45], 0, v[160:161]
	global_store_dwordx4 v[44:45], v[40:43], off
	s_waitcnt vmcnt(15)
	v_cvt_f32_f16_e32 v46, v216
	v_cvt_f32_f16_sdwa v47, v216 dst_sel:DWORD dst_unused:UNUSED_PAD src0_sel:WORD_1
	v_cvt_f32_f16_e32 v40, v214
	v_cvt_f32_f16_sdwa v41, v214 dst_sel:DWORD dst_unused:UNUSED_PAD src0_sel:WORD_1
	v_cvt_f32_f16_e32 v42, v215
	v_cvt_f32_f16_sdwa v43, v215 dst_sel:DWORD dst_unused:UNUSED_PAD src0_sel:WORD_1
	v_cvt_f32_f16_e32 v48, v217
	v_cvt_f32_f16_sdwa v49, v217 dst_sel:DWORD dst_unused:UNUSED_PAD src0_sel:WORD_1
	v_pk_fma_f32 v[36:37], v[40:41], s[24:25], v[36:37] op_sel_hi:[1,0,1]
	v_pk_fma_f32 v[38:39], v[42:43], s[24:25], v[38:39] op_sel_hi:[1,0,1]
	v_pk_fma_f32 v[40:41], v[48:49], s[24:25], v[34:35] op_sel_hi:[1,0,1]
	v_pk_fma_f32 v[34:35], v[46:47], s[24:25], v[32:33] op_sel_hi:[1,0,1]
	v_cvt_pk_f16_f32 v32, v36, v37
	v_cvt_pk_f16_f32 v33, v38, v39
	v_cvt_pk_f16_f32 v34, v34, v35
	v_cvt_pk_f16_f32 v35, v40, v41
	global_store_dwordx4 v[44:45], v[32:35], off offset:256
	s_waitcnt vmcnt(15)
; __device__ __forceinline__ u32x4 pack8h(const f32x4 a, const f32x4 b) { u32x4 w; w.x = cvt_pk_f16(a[0], a[1]); w.y = cvt_pk_f16(a[2], a[3]); w.z = cvt_pk_f16(b[0], b[1]); w.w = cvt_pk_f16(b[2], b[3]); return w; }
; #define PG8_FENCE asm volatile("" ::: "memory")
; #define PG8_BAR __builtin_amdgcn_s_barrier()
;     __device__ __forceinline__ void operator()(const f32x4 (&acc)[2][2][4][2], const Unit& u, int wr, int wc, int fr, int fq) const {
;     ...
; #pragma unroll
;             for (int m = 0; m < 4; ++m) { const size_t off = (size_t)(row0 + ai * HALF + m * 16) * 1024 + c0;
; #pragma unroll
;                 for (int bj = 0; bj < 2; ++bj) { f32x4 r0, r1; unpack8h(wx[m][bj], r0, r1);
;                     const f32x4 h0 = r0 * alpha + acc[ai][bj][m][0], h1 = r1 * alpha + acc[ai][bj][m][1];
;                     *(u32x4*)(XO + off + bj * HALF) = pack8h(h0, h1); } }
;             PG8_FENCE; }
;     ...
;         if constexpr (!Epi::AFTER_DRAIN) { E(acc, cur, wr, wc, fr, fq); S.done(cur); }
;         if (!has_next) break;
; #pragma unroll
;         for (int a = 0; a < 2; ++a)
; #pragma unroll
;             for (int b = 0; b < 2; ++b)
; #pragma unroll
;                 for (int m = 0; m < 4; ++m)
; #pragma unroll
;                     for (int n = 0; n < 2; ++n) acc[a][b][m][n] = (f32x4){0.f, 0.f, 0.f, 0.f};
;         cur = nxt; cA = nA; cB = nB; ++ui;
;         if constexpr (ALIGN_EPI) { if (wr == 1) PG8_BAR; }
	v_cvt_f32_f16_e32 v36, v220
	v_cvt_f32_f16_sdwa v37, v220 dst_sel:DWORD dst_unused:UNUSED_PAD src0_sel:WORD_1
	v_cvt_f32_f16_e32 v32, v218
	v_cvt_f32_f16_sdwa v33, v218 dst_sel:DWORD dst_unused:UNUSED_PAD src0_sel:WORD_1
	v_cvt_f32_f16_e32 v34, v219
	v_cvt_f32_f16_sdwa v35, v219 dst_sel:DWORD dst_unused:UNUSED_PAD src0_sel:WORD_1
	v_cvt_f32_f16_e32 v38, v221
	v_cvt_f32_f16_sdwa v39, v221 dst_sel:DWORD dst_unused:UNUSED_PAD src0_sel:WORD_1
	v_pk_fma_f32 v[28:29], v[32:33], s[24:25], v[28:29] op_sel_hi:[1,0,1]
	v_pk_fma_f32 v[30:31], v[34:35], s[24:25], v[30:31] op_sel_hi:[1,0,1]
	v_pk_fma_f32 v[32:33], v[38:39], s[24:25], v[26:27] op_sel_hi:[1,0,1]
	v_pk_fma_f32 v[26:27], v[36:37], s[24:25], v[24:25] op_sel_hi:[1,0,1]
	v_cvt_pk_f16_f32 v24, v28, v29
	v_lshl_add_u64 v[28:29], s[2:3], 0, v[104:105]
	v_cvt_pk_f16_f32 v25, v30, v31
	v_cvt_pk_f16_f32 v26, v26, v27
	v_cvt_pk_f16_f32 v27, v32, v33
	v_lshl_add_u64 v[28:29], v[28:29], 0, v[160:161]
	global_store_dwordx4 v[28:29], v[24:27], off
	s_waitcnt vmcnt(15)
	v_cvt_f32_f16_e32 v30, v224
	v_cvt_f32_f16_sdwa v31, v224 dst_sel:DWORD dst_unused:UNUSED_PAD src0_sel:WORD_1
	v_cvt_f32_f16_e32 v24, v222
	v_cvt_f32_f16_sdwa v25, v222 dst_sel:DWORD dst_unused:UNUSED_PAD src0_sel:WORD_1
	v_cvt_f32_f16_e32 v26, v223
	v_cvt_f32_f16_sdwa v27, v223 dst_sel:DWORD dst_unused:UNUSED_PAD src0_sel:WORD_1
	v_cvt_f32_f16_e32 v32, v225
	v_cvt_f32_f16_sdwa v33, v225 dst_sel:DWORD dst_unused:UNUSED_PAD src0_sel:WORD_1
	v_pk_fma_f32 v[20:21], v[24:25], s[24:25], v[20:21] op_sel_hi:[1,0,1]
	v_pk_fma_f32 v[22:23], v[26:27], s[24:25], v[22:23] op_sel_hi:[1,0,1]
	v_pk_fma_f32 v[24:25], v[32:33], s[24:25], v[18:19] op_sel_hi:[1,0,1]
	v_pk_fma_f32 v[18:19], v[30:31], s[24:25], v[16:17] op_sel_hi:[1,0,1]
	v_cvt_pk_f16_f32 v16, v20, v21
	v_cvt_pk_f16_f32 v17, v22, v23
	v_cvt_pk_f16_f32 v18, v18, v19
	v_cvt_pk_f16_f32 v19, v24, v25
	global_store_dwordx4 v[28:29], v[16:19], off offset:256
	s_waitcnt vmcnt(15)
	v_cvt_f32_f16_e32 v20, v228
	v_cvt_f32_f16_sdwa v21, v228 dst_sel:DWORD dst_unused:UNUSED_PAD src0_sel:WORD_1
	v_cvt_f32_f16_e32 v16, v226
	v_cvt_f32_f16_sdwa v17, v226 dst_sel:DWORD dst_unused:UNUSED_PAD src0_sel:WORD_1
	v_cvt_f32_f16_e32 v18, v227
	v_cvt_f32_f16_sdwa v19, v227 dst_sel:DWORD dst_unused:UNUSED_PAD src0_sel:WORD_1
	v_cvt_f32_f16_e32 v22, v229
	v_cvt_f32_f16_sdwa v23, v229 dst_sel:DWORD dst_unused:UNUSED_PAD src0_sel:WORD_1
	v_pk_fma_f32 v[12:13], v[16:17], s[24:25], v[12:13] op_sel_hi:[1,0,1]
	v_pk_fma_f32 v[14:15], v[18:19], s[24:25], v[14:15] op_sel_hi:[1,0,1]
	v_pk_fma_f32 v[16:17], v[22:23], s[24:25], v[10:11] op_sel_hi:[1,0,1]
	v_pk_fma_f32 v[10:11], v[20:21], s[24:25], v[8:9] op_sel_hi:[1,0,1]
	v_cvt_pk_f16_f32 v8, v12, v13
	v_lshl_add_u64 v[12:13], s[2:3], 0, v[74:75]
	v_cvt_pk_f16_f32 v9, v14, v15
	v_cvt_pk_f16_f32 v10, v10, v11
	v_cvt_pk_f16_f32 v11, v16, v17
	v_lshl_add_u64 v[12:13], v[12:13], 0, v[160:161]
	global_store_dwordx4 v[12:13], v[8:11], off
	s_waitcnt vmcnt(15)
	v_cvt_f32_f16_e32 v14, v244
	v_cvt_f32_f16_sdwa v15, v244 dst_sel:DWORD dst_unused:UNUSED_PAD src0_sel:WORD_1
	v_cvt_f32_f16_e32 v8, v242
	v_cvt_f32_f16_sdwa v9, v242 dst_sel:DWORD dst_unused:UNUSED_PAD src0_sel:WORD_1
	v_cvt_f32_f16_e32 v10, v243
	v_cvt_f32_f16_sdwa v11, v243 dst_sel:DWORD dst_unused:UNUSED_PAD src0_sel:WORD_1
	v_cvt_f32_f16_e32 v16, v245
	v_cvt_f32_f16_sdwa v17, v245 dst_sel:DWORD dst_unused:UNUSED_PAD src0_sel:WORD_1
	v_pk_fma_f32 v[4:5], v[8:9], s[24:25], v[4:5] op_sel_hi:[1,0,1]
	v_pk_fma_f32 v[6:7], v[10:11], s[24:25], v[6:7] op_sel_hi:[1,0,1]
	v_pk_fma_f32 v[8:9], v[16:17], s[24:25], v[2:3] op_sel_hi:[1,0,1]
	v_pk_fma_f32 v[2:3], v[14:15], s[24:25], v[0:1] op_sel_hi:[1,0,1]
	v_cvt_pk_f16_f32 v0, v4, v5
	v_cvt_pk_f16_f32 v1, v6, v7
	v_cvt_pk_f16_f32 v2, v2, v3
	v_cvt_pk_f16_f32 v3, v8, v9
	global_store_dwordx4 v[12:13], v[0:3], off offset:256
	s_mov_b64 s[24:25], -1
	s_cbranch_vccnz .LBB0_841
	s_andn2_b64 vcc, exec, s[0:1]
	s_cbranch_vccnz .LBB0_840
	s_barrier
	s_branch .LBB0_840
